# v42 plus nt cache policy on the prologue's once-read f32 weight and x loads
# speedup vs baseline: 1.0051x; 1.0051x over previous
.LBB0_444:
	s_lshl_b32 s28, s11, 12
	s_add_i32 s15, s11, 2
	s_add_i32 s17, s11, 4
	v_lshl_add_u64 v[14:15], s[28:29], 2, v[10:11]
	s_lshl_b32 s28, s15, 12
	s_lshl_b32 s30, s10, 12
	s_mov_b32 s31, s29
	s_add_i32 s49, s11, 6
	v_lshl_add_u64 v[18:19], s[28:29], 2, v[10:11]
	s_lshl_b32 s28, s17, 12
	s_add_i32 s16, s10, 2
	s_add_i32 s48, s10, 4
	s_add_i32 s50, s10, 6
	s_add_i32 s51, s11, 8
	s_add_i32 s52, s10, 8
	s_add_i32 s54, s10, 10
	s_add_i32 s56, s10, 12
	s_add_i32 s58, s10, 14
	v_lshl_add_u64 v[16:17], s[30:31], 2, v[10:11]
	global_load_dword v9, v[14:15], off nt
	global_load_dword v46, v[16:17], off nt
	v_lshl_add_u64 v[14:15], s[28:29], 2, v[10:11]
	s_lshl_b32 s28, s49, 12
	s_mov_b32 s35, s29
	s_mov_b32 s37, s29
	s_mov_b32 s39, s29
	s_mov_b32 s41, s29
	s_add_i32 s53, s11, 10
	s_mov_b32 s43, s29
	s_mov_b32 s45, s29
	s_mov_b32 s47, s29
	s_lshl_b32 s34, s16, 12
	s_lshl_b32 s36, s48, 12
	s_lshl_b32 s38, s50, 12
	s_lshl_b32 s40, s52, 12
	s_lshl_b32 s42, s54, 12
	s_lshl_b32 s44, s56, 12
	s_lshl_b32 s46, s58, 12
	v_lshl_add_u64 v[16:17], s[28:29], 2, v[10:11]
	s_lshl_b32 s28, s51, 12
	s_add_i32 s55, s11, 12
	v_lshl_add_u64 v[20:21], s[34:35], 2, v[10:11]
	v_lshl_add_u64 v[22:23], s[36:37], 2, v[10:11]
	v_lshl_add_u64 v[24:25], s[38:39], 2, v[10:11]
	v_lshl_add_u64 v[26:27], s[40:41], 2, v[10:11]
	v_lshl_add_u64 v[28:29], s[42:43], 2, v[10:11]
	v_lshl_add_u64 v[30:31], s[44:45], 2, v[10:11]
	v_lshl_add_u64 v[32:33], s[46:47], 2, v[10:11]
	global_load_dword v47, v[18:19], off nt
	global_load_dword v48, v[20:21], off nt
	global_load_dword v49, v[22:23], off nt
	global_load_dword v50, v[24:25], off nt
	global_load_dword v51, v[26:27], off nt
	global_load_dword v52, v[28:29], off nt
	global_load_dword v53, v[30:31], off nt
	global_load_dword v54, v[32:33], off nt
	global_load_dword v55, v[16:17], off nt
	global_load_dword v56, v[14:15], off nt
	v_lshl_add_u64 v[14:15], s[28:29], 2, v[10:11]
	s_lshl_b32 s28, s53, 12
	s_add_i32 s57, s11, 14
	v_lshl_add_u64 v[16:17], s[28:29], 2, v[10:11]
	s_lshl_b32 s28, s55, 12
	v_lshl_add_u64 v[18:19], s[28:29], 2, v[10:11]
	s_lshl_b32 s28, s57, 12
	v_lshl_add_u64 v[20:21], s[28:29], 2, v[10:11]
	global_load_dword v57, v[20:21], off nt
	global_load_dword v58, v[18:19], off nt
	global_load_dword v59, v[16:17], off nt
	global_load_dword v60, v[14:15], off nt
	s_lshl_b32 s13, s10, 1
	s_lshl_b32 s14, s11, 1
	v_or_b32_e32 v16, s13, v1
	v_or_b32_e32 v14, s14, v0
	s_add_i32 s11, s11, 16
	s_add_i32 s10, s10, 16
	s_add_i32 s12, s12, -16
	s_lshl_b32 s13, s16, 1
	s_lshl_b32 s16, s15, 1
	s_lshl_b32 s28, s48, 1
	s_lshl_b32 s17, s17, 1
	s_lshl_b32 s30, s50, 1
	s_lshl_b32 s31, s49, 1
	s_lshl_b32 s34, s52, 1
	s_lshl_b32 s35, s51, 1
	s_lshl_b32 s36, s54, 1
	s_lshl_b32 s37, s53, 1
	s_lshl_b32 s38, s56, 1
	s_lshl_b32 s39, s55, 1
	s_lshl_b32 s40, s58, 1
	s_lshl_b32 s41, s57, 1
	v_mad_u64_u32 v[14:15], s[14:15], v14, s27, v[4:5]
	v_mad_u64_u32 v[16:17], s[14:15], v16, s27, v[4:5]
	v_or_b32_e32 v15, s13, v1
	v_or_b32_e32 v17, s16, v0
	v_or_b32_e32 v24, s28, v1
	v_or_b32_e32 v22, s17, v0
	v_or_b32_e32 v28, s30, v1
	v_or_b32_e32 v26, s31, v0
	v_or_b32_e32 v32, s34, v1
	v_or_b32_e32 v30, s35, v0
	v_or_b32_e32 v36, s36, v1
	v_or_b32_e32 v34, s37, v0
	v_or_b32_e32 v40, s38, v1
	v_or_b32_e32 v38, s39, v0
	v_or_b32_e32 v44, s40, v1
	v_or_b32_e32 v42, s41, v0
	s_cmp_lg_u32 s12, 0
	v_mad_u64_u32 v[18:19], s[14:15], v17, s27, v[4:5]
	v_mad_u64_u32 v[20:21], s[14:15], v15, s27, v[4:5]
	v_mad_u64_u32 v[22:23], s[14:15], v22, s27, v[4:5]
	v_mad_u64_u32 v[24:25], s[14:15], v24, s27, v[4:5]
	v_mad_u64_u32 v[26:27], s[14:15], v26, s27, v[4:5]
	v_mad_u64_u32 v[28:29], s[14:15], v28, s27, v[4:5]
	v_mad_u64_u32 v[30:31], s[14:15], v30, s27, v[4:5]
	v_mad_u64_u32 v[32:33], s[14:15], v32, s27, v[4:5]
	v_mad_u64_u32 v[34:35], s[14:15], v34, s27, v[4:5]
	v_mad_u64_u32 v[36:37], s[14:15], v36, s27, v[4:5]
	v_mad_u64_u32 v[38:39], s[14:15], v38, s27, v[4:5]
	v_mad_u64_u32 v[40:41], s[14:15], v40, s27, v[4:5]
	v_mad_u64_u32 v[42:43], s[14:15], v42, s27, v[4:5]
	v_mad_u64_u32 v[44:45], s[14:15], v44, s27, v[4:5]
	s_waitcnt vmcnt(0)
	ds_write_b32 v14, v9
	ds_write_b32 v16, v46
	ds_write_b32 v18, v47
	ds_write_b32 v20, v48
	ds_write_b32 v22, v56
	ds_write_b32 v24, v49
	ds_write_b32 v26, v55
	ds_write_b32 v28, v50
	ds_write_b32 v30, v60
	ds_write_b32 v32, v51
	ds_write_b32 v34, v59
	ds_write_b32 v36, v52
	ds_write_b32 v38, v58
	ds_write_b32 v40, v53
	ds_write_b32 v42, v57
	ds_write_b32 v44, v54
	s_cbranch_scc1 .LBB0_444
	s_mul_i32 s11, s0, 0x1600000
	s_waitcnt lgkmcnt(0)
	s_mul_hi_i32 s10, s0, 0x1600000
	s_add_u32 s11, s86, s11
	v_readlane_b32 s12, v253, 43
	ds_read2_b32 v[18:19], v5 offset0:33 offset1:41
	ds_read2_b32 v[20:21], v5 offset1:8
	ds_read2_b32 v[22:23], v5 offset0:66 offset1:74
	ds_read2_b32 v[24:25], v5 offset0:99 offset1:107
	ds_read2_b32 v[26:27], v5 offset0:132 offset1:140
	ds_read2_b32 v[28:29], v5 offset0:165 offset1:173
	ds_read2_b32 v[30:31], v5 offset0:198 offset1:206
	ds_read2_b32 v[32:33], v5 offset0:231 offset1:239
	s_addc_u32 s12, s12, s10
	s_lshl_b32 s9, s9, 1
	s_add_u32 s10, s11, s9
	v_or_b32_e32 v9, s8, v3
	s_addc_u32 s11, s12, 0
	v_lshlrev_b32_e32 v10, 1, v6
	v_mov_b32_e32 v11, v85
	v_mul_u32_u24_e32 v9, 0x1600, v9
	v_lshl_add_u64 v[10:11], s[10:11], 0, v[10:11]
	v_lshlrev_b32_e32 v34, 1, v9
	v_mov_b32_e32 v35, v85
	s_waitcnt lgkmcnt(6)
	v_cvt_pk_bf16_f32 v14, v20, v18
	s_waitcnt lgkmcnt(4)
	v_cvt_pk_bf16_f32 v15, v22, v24
	s_waitcnt lgkmcnt(2)
	v_cvt_pk_bf16_f32 v16, v26, v28
	s_waitcnt lgkmcnt(0)
	v_cvt_pk_bf16_f32 v17, v30, v32
	v_lshl_add_u64 v[34:35], v[10:11], 0, v[34:35]
	global_store_dwordx4 v[34:35], v[14:17], off
	v_or_b32_e32 v9, s8, v7
	v_mul_u32_u24_e32 v9, 0x1600, v9
	v_cvt_pk_bf16_f32 v14, v21, v19
	v_cvt_pk_bf16_f32 v15, v23, v25
	v_cvt_pk_bf16_f32 v16, v27, v29
	v_cvt_pk_bf16_f32 v17, v31, v33
	ds_read2_b32 v[20:21], v5 offset0:16 offset1:24
	ds_read2_b32 v[22:23], v5 offset0:49 offset1:57
	ds_read2_b32 v[24:25], v5 offset0:82 offset1:90
	ds_read2_b32 v[26:27], v5 offset0:115 offset1:123
	ds_read2_b32 v[28:29], v5 offset0:148 offset1:156
	ds_read2_b32 v[30:31], v5 offset0:181 offset1:189
	ds_read2_b32 v[32:33], v5 offset0:214 offset1:222
	ds_read2_b32 v[34:35], v5 offset0:247 offset1:255
	v_lshlrev_b32_e32 v18, 1, v9
	v_mov_b32_e32 v19, v85
	v_or_b32_e32 v9, s8, v12
	v_lshl_add_u64 v[18:19], v[10:11], 0, v[18:19]
	v_mul_u32_u24_e32 v9, 0x1600, v9
	global_store_dwordx4 v[18:19], v[14:17], off
	v_lshlrev_b32_e32 v18, 1, v9
	v_mov_b32_e32 v19, v85
	v_or_b32_e32 v9, s8, v13
	s_waitcnt lgkmcnt(6)
	v_cvt_pk_bf16_f32 v14, v20, v22
	s_waitcnt lgkmcnt(4)
	v_cvt_pk_bf16_f32 v15, v24, v26
	s_waitcnt lgkmcnt(2)
	v_cvt_pk_bf16_f32 v16, v28, v30
	s_waitcnt lgkmcnt(0)
	v_cvt_pk_bf16_f32 v17, v32, v34
	v_lshl_add_u64 v[18:19], v[10:11], 0, v[18:19]
	v_mul_u32_u24_e32 v9, 0x1600, v9
	global_store_dwordx4 v[18:19], v[14:17], off
	v_lshlrev_b32_e32 v18, 1, v9
	v_mov_b32_e32 v19, v85
	v_cvt_pk_bf16_f32 v14, v21, v23
	v_cvt_pk_bf16_f32 v15, v25, v27
	v_cvt_pk_bf16_f32 v16, v29, v31
	v_cvt_pk_bf16_f32 v17, v33, v35
	v_lshl_add_u64 v[10:11], v[10:11], 0, v[18:19]
	global_store_dwordx4 v[10:11], v[14:17], off
	s_waitcnt lgkmcnt(0)
	v_readlane_b32 s50, v254, 61
	v_readlane_b32 s12, v255, 0
	s_mov_b64 s[30:31], 0
	v_readlane_b32 s51, v254, 62
	v_readlane_b32 s13, v255, 1
	s_movk_i32 s17, 0x1000

.LBB0_448:
	s_mul_i32 s30, s10, 0x5800
	s_mul_i32 s28, s11, 0x5800
	s_mov_b32 s31, s29
	s_mov_b32 s35, s29
	s_mov_b32 s37, s29
	s_mov_b32 s39, s29
	s_mov_b32 s41, s29
	s_mov_b32 s43, s29
	s_mov_b32 s45, s29
	s_mov_b32 s17, s29
	s_mov_b32 s47, s29
	s_mov_b32 s49, s29
	s_mov_b32 s51, s29
	s_mov_b32 s53, s29
	s_mov_b32 s55, s29
	s_mov_b32 s57, s29
	v_lshl_add_u64 v[14:15], s[28:29], 2, v[10:11]
	s_add_i32 s36, s30, 0xb000
	s_add_i32 s34, s28, 0xb000
	s_add_i32 s40, s30, 0x16000
	s_add_i32 s38, s28, 0x16000
	s_add_i32 s44, s30, 0x21000
	s_add_i32 s42, s28, 0x21000
	s_add_i32 s46, s30, 0x2c000
	s_add_i32 s16, s28, 0x2c000
	s_add_i32 s50, s30, 0x37000
	s_add_i32 s48, s28, 0x37000
	s_add_i32 s54, s30, 0x42000
	s_add_i32 s52, s28, 0x42000
	s_add_i32 s56, s30, 0x4d000
	s_add_i32 s28, s28, 0x4d000
	v_lshl_add_u64 v[16:17], s[30:31], 2, v[10:11]
	v_lshl_add_u64 v[18:19], s[34:35], 2, v[10:11]
	v_lshl_add_u64 v[20:21], s[36:37], 2, v[10:11]
	v_lshl_add_u64 v[22:23], s[38:39], 2, v[10:11]
	v_lshl_add_u64 v[24:25], s[40:41], 2, v[10:11]
	v_lshl_add_u64 v[26:27], s[42:43], 2, v[10:11]
	v_lshl_add_u64 v[28:29], s[44:45], 2, v[10:11]
	v_lshl_add_u64 v[30:31], s[16:17], 2, v[10:11]
	v_lshl_add_u64 v[32:33], s[46:47], 2, v[10:11]
	v_lshl_add_u64 v[34:35], s[48:49], 2, v[10:11]
	v_lshl_add_u64 v[36:37], s[50:51], 2, v[10:11]
	v_lshl_add_u64 v[38:39], s[52:53], 2, v[10:11]
	v_lshl_add_u64 v[40:41], s[54:55], 2, v[10:11]
	v_lshl_add_u64 v[42:43], s[28:29], 2, v[10:11]
	v_lshl_add_u64 v[44:45], s[56:57], 2, v[10:11]
	global_load_dword v9, v[14:15], off nt
	global_load_dword v46, v[16:17], off nt
	global_load_dword v47, v[18:19], off nt
	global_load_dword v48, v[20:21], off nt
	global_load_dword v49, v[22:23], off nt
	global_load_dword v50, v[24:25], off nt
	global_load_dword v51, v[26:27], off nt
	global_load_dword v52, v[28:29], off nt
	global_load_dword v53, v[30:31], off nt
	global_load_dword v54, v[32:33], off nt
	global_load_dword v55, v[34:35], off nt
	global_load_dword v56, v[36:37], off nt
	global_load_dword v57, v[38:39], off nt
	global_load_dword v58, v[40:41], off nt
	global_load_dword v59, v[42:43], off nt
	global_load_dword v60, v[44:45], off nt
	s_lshl_b32 s13, s10, 1
	s_lshl_b32 s14, s11, 1
	v_or_b32_e32 v16, s13, v1
	v_or_b32_e32 v14, s14, v0
	s_add_i32 s11, s11, 16
	s_add_i32 s10, s10, 16
	s_add_i32 s12, s12, -16
	s_add_i32 s16, s13, 4
	s_add_i32 s17, s14, 4
	s_add_i32 s28, s13, 8
	s_add_i32 s30, s14, 8
	s_add_i32 s31, s13, 12
	s_add_i32 s34, s14, 12
	s_add_i32 s35, s13, 16
	s_add_i32 s36, s14, 16
	s_add_i32 s37, s13, 20
	s_add_i32 s38, s14, 20
	s_add_i32 s39, s13, 24
	s_add_i32 s40, s14, 24
	s_add_i32 s13, s13, 28
	s_add_i32 s41, s14, 28
	v_mad_u64_u32 v[14:15], s[14:15], v14, s27, v[4:5]
	v_mad_u64_u32 v[16:17], s[14:15], v16, s27, v[4:5]
	v_or_b32_e32 v15, s16, v1
	v_or_b32_e32 v17, s17, v0
	v_or_b32_e32 v24, s28, v1
	v_or_b32_e32 v22, s30, v0
	v_or_b32_e32 v28, s31, v1
	v_or_b32_e32 v26, s34, v0
	v_or_b32_e32 v32, s35, v1
	v_or_b32_e32 v30, s36, v0
	v_or_b32_e32 v36, s37, v1
	v_or_b32_e32 v34, s38, v0
	v_or_b32_e32 v40, s39, v1
	v_or_b32_e32 v38, s40, v0
	v_or_b32_e32 v44, s13, v1
	v_or_b32_e32 v42, s41, v0
	s_cmp_lg_u32 s12, 0
	v_mad_u64_u32 v[18:19], s[14:15], v17, s27, v[4:5]
	v_mad_u64_u32 v[20:21], s[14:15], v15, s27, v[4:5]
	v_mad_u64_u32 v[22:23], s[14:15], v22, s27, v[4:5]
	v_mad_u64_u32 v[24:25], s[14:15], v24, s27, v[4:5]
	v_mad_u64_u32 v[26:27], s[14:15], v26, s27, v[4:5]
	v_mad_u64_u32 v[28:29], s[14:15], v28, s27, v[4:5]
	v_mad_u64_u32 v[30:31], s[14:15], v30, s27, v[4:5]
	v_mad_u64_u32 v[32:33], s[14:15], v32, s27, v[4:5]
	v_mad_u64_u32 v[34:35], s[14:15], v34, s27, v[4:5]
	v_mad_u64_u32 v[36:37], s[14:15], v36, s27, v[4:5]
	v_mad_u64_u32 v[38:39], s[14:15], v38, s27, v[4:5]
	v_mad_u64_u32 v[40:41], s[14:15], v40, s27, v[4:5]
	v_mad_u64_u32 v[42:43], s[14:15], v42, s27, v[4:5]
	v_mad_u64_u32 v[44:45], s[14:15], v44, s27, v[4:5]
	s_waitcnt vmcnt(0)
	ds_write_b32 v14, v9
	ds_write_b32 v16, v46
	ds_write_b32 v18, v47
	ds_write_b32 v20, v48
	ds_write_b32 v22, v49
	ds_write_b32 v24, v50
	ds_write_b32 v26, v51
	ds_write_b32 v28, v52
	ds_write_b32 v30, v53
	ds_write_b32 v32, v54
	ds_write_b32 v34, v55
	ds_write_b32 v36, v56
	ds_write_b32 v38, v57
	ds_write_b32 v40, v58
	ds_write_b32 v42, v59
	ds_write_b32 v44, v60
	s_cbranch_scc1 .LBB0_448
	v_readlane_b32 s10, v253, 44
	s_waitcnt lgkmcnt(0)
	s_add_u32 s7, s10, s7
	v_readlane_b32 s10, v253, 45
	ds_read2_b32 v[18:19], v5 offset0:33 offset1:41
	ds_read2_b32 v[20:21], v5 offset1:8
	ds_read2_b32 v[22:23], v5 offset0:66 offset1:74
	ds_read2_b32 v[24:25], v5 offset0:99 offset1:107
	ds_read2_b32 v[26:27], v5 offset0:132 offset1:140
	ds_read2_b32 v[28:29], v5 offset0:165 offset1:173
	ds_read2_b32 v[30:31], v5 offset0:198 offset1:206
	ds_read2_b32 v[32:33], v5 offset0:231 offset1:239
	s_addc_u32 s10, s10, s6
	s_and_b32 s9, 0xffff, s9
	s_lshl_b32 s6, s8, 1
	s_add_u32 s6, s7, s6
	s_addc_u32 s7, s10, 0
	v_lshlrev_b32_e32 v10, 1, v6
	v_mov_b32_e32 v11, v85
	v_or_b32_e32 v9, s9, v3
	v_lshl_add_u64 v[10:11], s[6:7], 0, v[10:11]
	v_lshlrev_b32_e32 v34, 12, v9
	v_mov_b32_e32 v35, v85
	s_waitcnt lgkmcnt(6)
	v_cvt_pk_bf16_f32 v14, v20, v18
	s_waitcnt lgkmcnt(4)
	v_cvt_pk_bf16_f32 v15, v22, v24
	s_waitcnt lgkmcnt(2)
	v_cvt_pk_bf16_f32 v16, v26, v28
	s_waitcnt lgkmcnt(0)
	v_cvt_pk_bf16_f32 v17, v30, v32
	v_lshl_add_u64 v[34:35], v[10:11], 0, v[34:35]
	global_store_dwordx4 v[34:35], v[14:17], off
	v_lshlrev_b32_e32 v110, 16, v14
	v_and_b32_e32 v111, 0xffff0000, v14
	v_lshlrev_b32_e32 v112, 16, v15
	v_and_b32_e32 v113, 0xffff0000, v15
	v_lshlrev_b32_e32 v114, 16, v16
	v_and_b32_e32 v115, 0xffff0000, v16
	v_lshlrev_b32_e32 v116, 16, v17
	v_and_b32_e32 v117, 0xffff0000, v17
	v_mul_f32_e32 v118, v94, v110
	v_mul_f32_e32 v119, v102, v110
	v_fmac_f32_e32 v118, v95, v111
	v_fmac_f32_e32 v119, v103, v111
	v_fmac_f32_e32 v118, v96, v112
	v_fmac_f32_e32 v119, v104, v112
	v_fmac_f32_e32 v118, v97, v113
	v_fmac_f32_e32 v119, v105, v113
	v_fmac_f32_e32 v118, v98, v114
	v_fmac_f32_e32 v119, v106, v114
	v_fmac_f32_e32 v118, v99, v115
	v_fmac_f32_e32 v119, v107, v115
	v_fmac_f32_e32 v118, v100, v116
	v_fmac_f32_e32 v119, v108, v116
	v_fmac_f32_e32 v118, v101, v117
	v_fmac_f32_e32 v119, v109, v117
	v_or_b32_e32 v9, s9, v7
	v_lshlrev_b32_e32 v18, 12, v9
	v_cvt_pk_bf16_f32 v14, v21, v19
	v_cvt_pk_bf16_f32 v15, v23, v25
	v_cvt_pk_bf16_f32 v16, v27, v29
	v_cvt_pk_bf16_f32 v17, v31, v33
	ds_read2_b32 v[20:21], v5 offset0:49 offset1:57
	ds_read2_b32 v[22:23], v5 offset0:16 offset1:24
	ds_read2_b32 v[24:25], v5 offset0:82 offset1:90
	ds_read2_b32 v[26:27], v5 offset0:115 offset1:123
	ds_read2_b32 v[28:29], v5 offset0:148 offset1:156
	ds_read2_b32 v[30:31], v5 offset0:181 offset1:189
	ds_read2_b32 v[32:33], v5 offset0:214 offset1:222
	ds_read2_b32 v[34:35], v5 offset0:247 offset1:255
	v_mov_b32_e32 v19, v85
	v_lshl_add_u64 v[18:19], v[10:11], 0, v[18:19]
	v_or_b32_e32 v9, s9, v12
	global_store_dwordx4 v[18:19], v[14:17], off
	v_lshlrev_b32_e32 v110, 16, v14
	v_and_b32_e32 v111, 0xffff0000, v14
	v_lshlrev_b32_e32 v112, 16, v15
	v_and_b32_e32 v113, 0xffff0000, v15
	v_lshlrev_b32_e32 v114, 16, v16
	v_and_b32_e32 v115, 0xffff0000, v16
	v_lshlrev_b32_e32 v116, 16, v17
	v_and_b32_e32 v117, 0xffff0000, v17
	v_mul_f32_e32 v120, v94, v110
	v_mul_f32_e32 v121, v102, v110
	v_fmac_f32_e32 v120, v95, v111
	v_fmac_f32_e32 v121, v103, v111
	v_fmac_f32_e32 v120, v96, v112
	v_fmac_f32_e32 v121, v104, v112
	v_fmac_f32_e32 v120, v97, v113
	v_fmac_f32_e32 v121, v105, v113
	v_fmac_f32_e32 v120, v98, v114
	v_fmac_f32_e32 v121, v106, v114
	v_fmac_f32_e32 v120, v99, v115
	v_fmac_f32_e32 v121, v107, v115
	v_fmac_f32_e32 v120, v100, v116
	v_fmac_f32_e32 v121, v108, v116
	v_fmac_f32_e32 v120, v101, v117
	v_fmac_f32_e32 v121, v109, v117
	v_lshlrev_b32_e32 v18, 12, v9
	v_mov_b32_e32 v19, v85
	s_waitcnt lgkmcnt(6)
	v_cvt_pk_bf16_f32 v14, v22, v20
	s_waitcnt lgkmcnt(4)
	v_cvt_pk_bf16_f32 v15, v24, v26
	s_waitcnt lgkmcnt(2)
	v_cvt_pk_bf16_f32 v16, v28, v30
	s_waitcnt lgkmcnt(0)
	v_cvt_pk_bf16_f32 v17, v32, v34
	v_lshl_add_u64 v[18:19], v[10:11], 0, v[18:19]
	v_or_b32_e32 v9, s9, v13
	global_store_dwordx4 v[18:19], v[14:17], off
	v_lshlrev_b32_e32 v110, 16, v14
	v_and_b32_e32 v111, 0xffff0000, v14
	v_lshlrev_b32_e32 v112, 16, v15
	v_and_b32_e32 v113, 0xffff0000, v15
	v_lshlrev_b32_e32 v114, 16, v16
	v_and_b32_e32 v115, 0xffff0000, v16
	v_lshlrev_b32_e32 v116, 16, v17
	v_and_b32_e32 v117, 0xffff0000, v17
	v_mul_f32_e32 v122, v94, v110
	v_mul_f32_e32 v123, v102, v110
	v_fmac_f32_e32 v122, v95, v111
	v_fmac_f32_e32 v123, v103, v111
	v_fmac_f32_e32 v122, v96, v112
	v_fmac_f32_e32 v123, v104, v112
	v_fmac_f32_e32 v122, v97, v113
	v_fmac_f32_e32 v123, v105, v113
	v_fmac_f32_e32 v122, v98, v114
	v_fmac_f32_e32 v123, v106, v114
	v_fmac_f32_e32 v122, v99, v115
	v_fmac_f32_e32 v123, v107, v115
	v_fmac_f32_e32 v122, v100, v116
	v_fmac_f32_e32 v123, v108, v116
	v_fmac_f32_e32 v122, v101, v117
	v_fmac_f32_e32 v123, v109, v117
	v_lshlrev_b32_e32 v18, 12, v9
	v_mov_b32_e32 v19, v85
	v_cvt_pk_bf16_f32 v14, v23, v21
	v_cvt_pk_bf16_f32 v15, v25, v27
	v_cvt_pk_bf16_f32 v16, v29, v31
	v_cvt_pk_bf16_f32 v17, v33, v35
	v_lshl_add_u64 v[10:11], v[10:11], 0, v[18:19]
	global_store_dwordx4 v[10:11], v[14:17], off
	v_lshlrev_b32_e32 v110, 16, v14
	v_and_b32_e32 v111, 0xffff0000, v14
	v_lshlrev_b32_e32 v112, 16, v15
	v_and_b32_e32 v113, 0xffff0000, v15
	v_lshlrev_b32_e32 v114, 16, v16
	v_and_b32_e32 v115, 0xffff0000, v16
	v_lshlrev_b32_e32 v116, 16, v17
	v_and_b32_e32 v117, 0xffff0000, v17
	v_mul_f32_e32 v124, v94, v110
	v_mul_f32_e32 v125, v102, v110
	v_fmac_f32_e32 v124, v95, v111
	v_fmac_f32_e32 v125, v103, v111
	v_fmac_f32_e32 v124, v96, v112
	v_fmac_f32_e32 v125, v104, v112
	v_fmac_f32_e32 v124, v97, v113
	v_fmac_f32_e32 v125, v105, v113
	v_fmac_f32_e32 v124, v98, v114
	v_fmac_f32_e32 v125, v106, v114
	v_fmac_f32_e32 v124, v99, v115
	v_fmac_f32_e32 v125, v107, v115
	v_fmac_f32_e32 v124, v100, v116
	v_fmac_f32_e32 v125, v108, v116
	v_fmac_f32_e32 v124, v101, v117
	v_fmac_f32_e32 v125, v109, v117
	v_add_f32_dpp v118, v118, v118 quad_perm:[1,0,3,2] row_mask:0xf bank_mask:0xf
	v_add_f32_dpp v119, v119, v119 quad_perm:[1,0,3,2] row_mask:0xf bank_mask:0xf
	v_add_f32_dpp v120, v120, v120 quad_perm:[1,0,3,2] row_mask:0xf bank_mask:0xf
	v_add_f32_dpp v121, v121, v121 quad_perm:[1,0,3,2] row_mask:0xf bank_mask:0xf
	v_add_f32_dpp v122, v122, v122 quad_perm:[1,0,3,2] row_mask:0xf bank_mask:0xf
	v_add_f32_dpp v123, v123, v123 quad_perm:[1,0,3,2] row_mask:0xf bank_mask:0xf
	v_add_f32_dpp v124, v124, v124 quad_perm:[1,0,3,2] row_mask:0xf bank_mask:0xf
	v_add_f32_dpp v125, v125, v125 quad_perm:[1,0,3,2] row_mask:0xf bank_mask:0xf
	v_add_f32_dpp v118, v118, v118 quad_perm:[2,3,0,1] row_mask:0xf bank_mask:0xf
	v_add_f32_dpp v119, v119, v119 quad_perm:[2,3,0,1] row_mask:0xf bank_mask:0xf
	v_add_f32_dpp v120, v120, v120 quad_perm:[2,3,0,1] row_mask:0xf bank_mask:0xf
	v_add_f32_dpp v121, v121, v121 quad_perm:[2,3,0,1] row_mask:0xf bank_mask:0xf
	v_add_f32_dpp v122, v122, v122 quad_perm:[2,3,0,1] row_mask:0xf bank_mask:0xf
	v_add_f32_dpp v123, v123, v123 quad_perm:[2,3,0,1] row_mask:0xf bank_mask:0xf
	v_add_f32_dpp v124, v124, v124 quad_perm:[2,3,0,1] row_mask:0xf bank_mask:0xf
	v_add_f32_dpp v125, v125, v125 quad_perm:[2,3,0,1] row_mask:0xf bank_mask:0xf
	v_add_f32_dpp v118, v118, v118 row_half_mirror row_mask:0xf bank_mask:0xf
	v_add_f32_dpp v119, v119, v119 row_half_mirror row_mask:0xf bank_mask:0xf
	v_add_f32_dpp v120, v120, v120 row_half_mirror row_mask:0xf bank_mask:0xf
	v_add_f32_dpp v121, v121, v121 row_half_mirror row_mask:0xf bank_mask:0xf
	v_add_f32_dpp v122, v122, v122 row_half_mirror row_mask:0xf bank_mask:0xf
	v_add_f32_dpp v123, v123, v123 row_half_mirror row_mask:0xf bank_mask:0xf
	v_add_f32_dpp v124, v124, v124 row_half_mirror row_mask:0xf bank_mask:0xf
	v_add_f32_dpp v125, v125, v125 row_half_mirror row_mask:0xf bank_mask:0xf
	v_cmp_eq_u32_e32 vcc, 0, v6
	s_and_saveexec_b64 s[36:37], vcc
	s_lshl_b32 s100, s0, 5
	s_lshr_b32 s101, s8, 6
	s_add_i32 s100, s100, s101
	s_mul_i32 s100, s100, 0x2c00
	s_and_b32 s101, s9, 0xffff
	s_add_i32 s100, s100, s101
	s_lshl_b32 s100, s100, 3
	s_add_u32 s38, s20, 0x1a000000
	s_addc_u32 s39, s21, 0
	v_lshlrev_b32_e32 v126, 3, v3
	v_add_u32_e32 v126, s100, v126
	global_store_dwordx2 v126, v[118:119], s[38:39]
	global_store_dwordx2 v126, v[120:121], s[38:39] offset:64
	global_store_dwordx2 v126, v[122:123], s[38:39] offset:128
	global_store_dwordx2 v126, v[124:125], s[38:39] offset:192
	s_or_b64 exec, exec, s[36:37]
	s_waitcnt lgkmcnt(0)
	v_readlane_b32 s50, v254, 61
	v_readlane_b32 s12, v255, 0
	s_movk_i32 s17, 0x1000
	v_readlane_b32 s51, v254, 62
	v_readlane_b32 s13, v255, 1

.LBB0_453:
	s_lshl_b32 s28, s8, 12
	s_add_i32 s12, s8, 2
	s_add_i32 s46, s8, 4
	v_lshl_add_u64 v[14:15], s[28:29], 2, v[10:11]
	s_lshl_b32 s28, s12, 12
	s_lshl_b32 s34, s7, 12
	s_mov_b32 s35, s29
	s_add_i32 s48, s8, 6
	v_lshl_add_u64 v[18:19], s[28:29], 2, v[10:11]
	s_lshl_b32 s28, s46, 12
	s_add_i32 s13, s7, 2
	s_add_i32 s47, s7, 4
	s_add_i32 s49, s7, 6
	s_add_i32 s50, s8, 8
	s_add_i32 s51, s7, 8
	s_add_i32 s53, s7, 10
	s_add_i32 s55, s7, 12
	s_add_i32 s57, s7, 14
	v_lshl_add_u64 v[16:17], s[34:35], 2, v[10:11]
	global_load_dword v9, v[14:15], off nt
	global_load_dword v46, v[16:17], off nt
	v_lshl_add_u64 v[14:15], s[28:29], 2, v[10:11]
	s_lshl_b32 s28, s48, 12
	s_mov_b32 s37, s29
	s_mov_b32 s39, s29
	s_mov_b32 s41, s29
	s_mov_b32 s15, s29
	s_add_i32 s52, s8, 10
	s_mov_b32 s17, s29
	s_mov_b32 s43, s29
	s_mov_b32 s45, s29
	s_lshl_b32 s36, s13, 12
	s_lshl_b32 s38, s47, 12
	s_lshl_b32 s40, s49, 12
	s_lshl_b32 s14, s51, 12
	s_lshl_b32 s16, s53, 12
	s_lshl_b32 s42, s55, 12
	s_lshl_b32 s44, s57, 12
	v_lshl_add_u64 v[16:17], s[28:29], 2, v[10:11]
	s_lshl_b32 s28, s50, 12
	s_add_i32 s54, s8, 12
	v_lshl_add_u64 v[20:21], s[36:37], 2, v[10:11]
	v_lshl_add_u64 v[22:23], s[38:39], 2, v[10:11]
	v_lshl_add_u64 v[24:25], s[40:41], 2, v[10:11]
	v_lshl_add_u64 v[26:27], s[14:15], 2, v[10:11]
	v_lshl_add_u64 v[28:29], s[16:17], 2, v[10:11]
	v_lshl_add_u64 v[30:31], s[42:43], 2, v[10:11]
	v_lshl_add_u64 v[32:33], s[44:45], 2, v[10:11]
	global_load_dword v47, v[18:19], off nt
	global_load_dword v48, v[20:21], off nt
	global_load_dword v49, v[22:23], off nt
	global_load_dword v50, v[24:25], off nt
	global_load_dword v51, v[26:27], off nt
	global_load_dword v52, v[28:29], off nt
	global_load_dword v53, v[30:31], off nt
	global_load_dword v54, v[32:33], off nt
	global_load_dword v55, v[16:17], off nt
	global_load_dword v56, v[14:15], off nt
	v_lshl_add_u64 v[14:15], s[28:29], 2, v[10:11]
	s_lshl_b32 s28, s52, 12
	s_add_i32 s56, s8, 14
	v_lshl_add_u64 v[16:17], s[28:29], 2, v[10:11]
	s_lshl_b32 s28, s54, 12
	v_lshl_add_u64 v[18:19], s[28:29], 2, v[10:11]
	s_lshl_b32 s28, s56, 12
	v_lshl_add_u64 v[20:21], s[28:29], 2, v[10:11]
	global_load_dword v57, v[20:21], off nt
	global_load_dword v58, v[18:19], off nt
	global_load_dword v59, v[16:17], off nt
	global_load_dword v60, v[14:15], off nt
	s_lshl_b32 s10, s7, 1
	s_lshl_b32 s11, s8, 1
	v_or_b32_e32 v16, s10, v1
	v_or_b32_e32 v14, s11, v0
	s_add_i32 s8, s8, 16
	s_add_i32 s7, s7, 16
	s_add_i32 s9, s9, -16
	s_lshl_b32 s13, s13, 1
	s_lshl_b32 s12, s12, 1
	s_lshl_b32 s14, s47, 1
	s_lshl_b32 s15, s46, 1
	s_lshl_b32 s16, s49, 1
	s_lshl_b32 s17, s48, 1
	s_lshl_b32 s28, s51, 1
	s_lshl_b32 s34, s50, 1
	s_lshl_b32 s35, s53, 1
	s_lshl_b32 s36, s52, 1
	s_lshl_b32 s37, s55, 1
	s_lshl_b32 s38, s54, 1
	s_lshl_b32 s39, s57, 1
	s_lshl_b32 s40, s56, 1
	v_mad_u64_u32 v[14:15], s[10:11], v14, s27, v[4:5]
	v_mad_u64_u32 v[16:17], s[10:11], v16, s27, v[4:5]
	v_or_b32_e32 v15, s13, v1
	v_or_b32_e32 v17, s12, v0
	v_or_b32_e32 v24, s14, v1
	v_or_b32_e32 v22, s15, v0
	v_or_b32_e32 v28, s16, v1
	v_or_b32_e32 v26, s17, v0
	v_or_b32_e32 v32, s28, v1
	v_or_b32_e32 v30, s34, v0
	v_or_b32_e32 v36, s35, v1
	v_or_b32_e32 v34, s36, v0
	v_or_b32_e32 v40, s37, v1
	v_or_b32_e32 v38, s38, v0
	v_or_b32_e32 v44, s39, v1
	v_or_b32_e32 v42, s40, v0
	s_cmp_lg_u32 s9, 0
	v_mad_u64_u32 v[18:19], s[10:11], v17, s27, v[4:5]
	v_mad_u64_u32 v[20:21], s[10:11], v15, s27, v[4:5]
	v_mad_u64_u32 v[22:23], s[10:11], v22, s27, v[4:5]
	v_mad_u64_u32 v[24:25], s[10:11], v24, s27, v[4:5]
	v_mad_u64_u32 v[26:27], s[10:11], v26, s27, v[4:5]
	v_mad_u64_u32 v[28:29], s[10:11], v28, s27, v[4:5]
	v_mad_u64_u32 v[30:31], s[10:11], v30, s27, v[4:5]
	v_mad_u64_u32 v[32:33], s[10:11], v32, s27, v[4:5]
	v_mad_u64_u32 v[34:35], s[10:11], v34, s27, v[4:5]
	v_mad_u64_u32 v[36:37], s[10:11], v36, s27, v[4:5]
	v_mad_u64_u32 v[38:39], s[10:11], v38, s27, v[4:5]
	v_mad_u64_u32 v[40:41], s[10:11], v40, s27, v[4:5]
	v_mad_u64_u32 v[42:43], s[10:11], v42, s27, v[4:5]
	v_mad_u64_u32 v[44:45], s[10:11], v44, s27, v[4:5]
	s_waitcnt vmcnt(0)
	ds_write_b32 v14, v9
	ds_write_b32 v16, v46
	ds_write_b32 v18, v47
	ds_write_b32 v20, v48
	ds_write_b32 v22, v56
	ds_write_b32 v24, v49
	ds_write_b32 v26, v55
	ds_write_b32 v28, v50
	ds_write_b32 v30, v60
	ds_write_b32 v32, v51
	ds_write_b32 v34, v59
	ds_write_b32 v36, v52
	ds_write_b32 v38, v58
	ds_write_b32 v40, v53
	ds_write_b32 v42, v57
	ds_write_b32 v44, v54
	s_cbranch_scc1 .LBB0_453
; #define LAS __attribute__((address_space(3)))
; __device__ __forceinline__ unsigned cvtpk(float lo, float hi) { return pg8::cvt_pk_bf16(lo, hi); }
; __device__ __forceinline__ void transpose_item(const float* __restrict__ W, int K, int N, bf16* __restrict__ WT, LAS float* scr, int item, int lane) {
;     ...
;     asm volatile("s_waitcnt lgkmcnt(0)" ::: "memory");
;     const int c = lane & 7;
; #pragma unroll
;     for (int j = 0; j < 4; ++j) { const int n = (lane >> 3) + 8 * j; const LAS float* s = scr + (8 * c) * 33 + n;
;         v4u o; o.x = cvtpk(s[0 * 33], s[1 * 33]); o.y = cvtpk(s[2 * 33], s[3 * 33]); o.z = cvtpk(s[4 * 33], s[5 * 33]); o.w = cvtpk(s[6 * 33], s[7 * 33]);
;         *(v4u*)(WT + (size_t)(n0 + n) * K + k0 + 8 * c) = o; }
;     asm volatile("s_waitcnt lgkmcnt(0)" ::: "memory");
	s_lshl_b64 s[8:9], s[30:31], 1
	v_readlane_b32 s7, v253, 46
	s_waitcnt lgkmcnt(0)
	s_add_u32 s7, s7, s8
	v_readlane_b32 s8, v253, 47
	ds_read2_b32 v[18:19], v5 offset0:33 offset1:41
	ds_read2_b32 v[20:21], v5 offset1:8
	ds_read2_b32 v[22:23], v5 offset0:66 offset1:74
	ds_read2_b32 v[24:25], v5 offset0:99 offset1:107
	ds_read2_b32 v[26:27], v5 offset0:132 offset1:140
	ds_read2_b32 v[28:29], v5 offset0:165 offset1:173
	ds_read2_b32 v[30:31], v5 offset0:198 offset1:206
	ds_read2_b32 v[32:33], v5 offset0:231 offset1:239
	s_addc_u32 s8, s8, s9
	s_lshl_b32 s6, s6, 1
	s_add_u32 s6, s7, s6
	s_addc_u32 s7, s8, 0
	v_lshlrev_b32_e32 v10, 1, v6
	v_mov_b32_e32 v11, v85
	v_or_b32_e32 v9, s1, v3
	v_lshl_add_u64 v[10:11], s[6:7], 0, v[10:11]
	v_lshlrev_b32_e32 v34, 12, v9
	v_mov_b32_e32 v35, v85
	s_waitcnt lgkmcnt(6)
	v_cvt_pk_bf16_f32 v14, v20, v18
	s_waitcnt lgkmcnt(4)
	v_cvt_pk_bf16_f32 v15, v22, v24
	s_waitcnt lgkmcnt(2)
	v_cvt_pk_bf16_f32 v16, v26, v28
	s_waitcnt lgkmcnt(0)
	v_cvt_pk_bf16_f32 v17, v30, v32
	v_lshl_add_u64 v[34:35], v[10:11], 0, v[34:35]
	global_store_dwordx4 v[34:35], v[14:17], off
	v_or_b32_e32 v9, s1, v7
	v_lshlrev_b32_e32 v18, 12, v9
	v_cvt_pk_bf16_f32 v14, v21, v19
	v_cvt_pk_bf16_f32 v15, v23, v25
	v_cvt_pk_bf16_f32 v16, v27, v29
	v_cvt_pk_bf16_f32 v17, v31, v33
	ds_read2_b32 v[20:21], v5 offset0:49 offset1:57
	ds_read2_b32 v[22:23], v5 offset0:16 offset1:24
	ds_read2_b32 v[24:25], v5 offset0:82 offset1:90
	ds_read2_b32 v[26:27], v5 offset0:115 offset1:123
	ds_read2_b32 v[28:29], v5 offset0:148 offset1:156
	ds_read2_b32 v[30:31], v5 offset0:181 offset1:189
	ds_read2_b32 v[32:33], v5 offset0:214 offset1:222
	ds_read2_b32 v[34:35], v5 offset0:247 offset1:255
	v_mov_b32_e32 v19, v85
	v_lshl_add_u64 v[18:19], v[10:11], 0, v[18:19]
	v_or_b32_e32 v9, s1, v12
	global_store_dwordx4 v[18:19], v[14:17], off
	v_lshlrev_b32_e32 v18, 12, v9
	v_mov_b32_e32 v19, v85
	s_waitcnt lgkmcnt(6)
	v_cvt_pk_bf16_f32 v14, v22, v20
	s_waitcnt lgkmcnt(4)
	v_cvt_pk_bf16_f32 v15, v24, v26
	s_waitcnt lgkmcnt(2)
	v_cvt_pk_bf16_f32 v16, v28, v30
	s_waitcnt lgkmcnt(0)
	v_cvt_pk_bf16_f32 v17, v32, v34
	v_lshl_add_u64 v[18:19], v[10:11], 0, v[18:19]
	v_or_b32_e32 v9, s1, v13
	global_store_dwordx4 v[18:19], v[14:17], off
	v_lshlrev_b32_e32 v18, 12, v9
	v_mov_b32_e32 v19, v85
	v_cvt_pk_bf16_f32 v14, v23, v21
	v_cvt_pk_bf16_f32 v15, v25, v27
	v_cvt_pk_bf16_f32 v16, v29, v31
	v_cvt_pk_bf16_f32 v17, v33, v35
	v_lshl_add_u64 v[10:11], v[10:11], 0, v[18:19]
	global_store_dwordx4 v[10:11], v[14:17], off
	s_waitcnt lgkmcnt(0)
	v_readlane_b32 s50, v254, 61
	v_readlane_b32 s12, v255, 0
	s_movk_i32 s17, 0x1000
	v_readlane_b32 s51, v254, 62
	v_readlane_b32 s13, v255, 1

; __device__ __forceinline__ void transpose_item(const float* __restrict__ W, int K, int N, bf16* __restrict__ WT, LAS float* scr, int item, int lane) {
;     ...
; #pragma unroll 8
;     for (int i = 0; i < 32; ++i) { const int kk = 2 * i + (lane >> 5); scr[kk * 33 + (lane & 31)] = (Wb + (size_t)(2 * i) * N)[loff]; }
.LBB0_457:
	s_mul_i32 s36, s1, 0x2800
	s_mul_i32 s28, s5, 0x2800
	s_mov_b32 s37, s29
	s_mov_b32 s39, s29
	s_mov_b32 s41, s29
	s_mov_b32 s43, s29
	s_mov_b32 s45, s29
	s_mov_b32 s47, s29
	s_mov_b32 s49, s29
	s_mov_b32 s11, s29
	s_mov_b32 s13, s29
	s_mov_b32 s15, s29
	s_mov_b32 s17, s29
	s_mov_b32 s51, s29
	s_mov_b32 s53, s29
	s_mov_b32 s55, s29
	v_lshl_add_u64 v[14:15], s[28:29], 2, v[10:11]
	s_add_i32 s40, s36, 0x5000
	s_add_i32 s38, s28, 0x5000
	s_add_i32 s44, s36, 0xa000
	s_add_i32 s42, s28, 0xa000
	s_add_i32 s48, s36, 0xf000
	s_add_i32 s46, s28, 0xf000
	s_add_i32 s12, s36, 0x14000
	s_add_i32 s10, s28, 0x14000
	s_add_i32 s16, s36, 0x19000
	s_add_i32 s14, s28, 0x19000
	s_add_i32 s52, s36, 0x1e000
	s_add_i32 s50, s28, 0x1e000
	s_add_i32 s54, s36, 0x23000
	s_add_i32 s28, s28, 0x23000
	v_lshl_add_u64 v[16:17], s[36:37], 2, v[10:11]
	v_lshl_add_u64 v[18:19], s[38:39], 2, v[10:11]
	v_lshl_add_u64 v[20:21], s[40:41], 2, v[10:11]
	v_lshl_add_u64 v[22:23], s[42:43], 2, v[10:11]
	v_lshl_add_u64 v[24:25], s[44:45], 2, v[10:11]
	v_lshl_add_u64 v[26:27], s[46:47], 2, v[10:11]
	v_lshl_add_u64 v[28:29], s[48:49], 2, v[10:11]
	v_lshl_add_u64 v[30:31], s[10:11], 2, v[10:11]
	v_lshl_add_u64 v[32:33], s[12:13], 2, v[10:11]
	v_lshl_add_u64 v[34:35], s[14:15], 2, v[10:11]
	v_lshl_add_u64 v[36:37], s[16:17], 2, v[10:11]
	v_lshl_add_u64 v[38:39], s[50:51], 2, v[10:11]
	v_lshl_add_u64 v[40:41], s[52:53], 2, v[10:11]
	v_lshl_add_u64 v[42:43], s[28:29], 2, v[10:11]
	v_lshl_add_u64 v[44:45], s[54:55], 2, v[10:11]
	global_load_dword v9, v[14:15], off nt
	global_load_dword v46, v[16:17], off nt
	global_load_dword v47, v[18:19], off nt
	global_load_dword v48, v[20:21], off nt
	global_load_dword v49, v[22:23], off nt
	global_load_dword v50, v[24:25], off nt
	global_load_dword v51, v[26:27], off nt
	global_load_dword v52, v[28:29], off nt
	global_load_dword v53, v[30:31], off nt
	global_load_dword v54, v[32:33], off nt
	global_load_dword v55, v[34:35], off nt
	global_load_dword v56, v[36:37], off nt
	global_load_dword v57, v[38:39], off nt
	global_load_dword v58, v[40:41], off nt
	global_load_dword v59, v[42:43], off nt
	global_load_dword v60, v[44:45], off nt
	s_lshl_b32 s7, s1, 1
	s_lshl_b32 s8, s5, 1
	v_or_b32_e32 v16, s7, v1
	v_or_b32_e32 v14, s8, v0
	s_add_i32 s5, s5, 16
	s_add_i32 s1, s1, 16
	s_add_i32 s6, s6, -16
	s_add_i32 s10, s7, 4
	s_add_i32 s11, s8, 4
	s_add_i32 s12, s7, 8
	s_add_i32 s13, s8, 8
	s_add_i32 s14, s7, 12
	s_add_i32 s15, s8, 12
	s_add_i32 s16, s7, 16
	s_add_i32 s17, s8, 16
	s_add_i32 s28, s7, 20
	s_add_i32 s31, s8, 20
	s_add_i32 s36, s7, 24
	s_add_i32 s37, s8, 24
	s_add_i32 s7, s7, 28
	s_add_i32 s38, s8, 28
	v_mad_u64_u32 v[14:15], s[8:9], v14, s27, v[4:5]
	v_mad_u64_u32 v[16:17], s[8:9], v16, s27, v[4:5]
	v_or_b32_e32 v15, s10, v1
	v_or_b32_e32 v17, s11, v0
	v_or_b32_e32 v24, s12, v1
	v_or_b32_e32 v22, s13, v0
	v_or_b32_e32 v28, s14, v1
	v_or_b32_e32 v26, s15, v0
	v_or_b32_e32 v32, s16, v1
	v_or_b32_e32 v30, s17, v0
	v_or_b32_e32 v36, s28, v1
	v_or_b32_e32 v34, s31, v0
	v_or_b32_e32 v40, s36, v1
	v_or_b32_e32 v38, s37, v0
	v_or_b32_e32 v44, s7, v1
	v_or_b32_e32 v42, s38, v0
	s_cmp_lg_u32 s6, 0
	v_mad_u64_u32 v[18:19], s[8:9], v17, s27, v[4:5]
	v_mad_u64_u32 v[20:21], s[8:9], v15, s27, v[4:5]
	v_mad_u64_u32 v[22:23], s[8:9], v22, s27, v[4:5]
	v_mad_u64_u32 v[24:25], s[8:9], v24, s27, v[4:5]
	v_mad_u64_u32 v[26:27], s[8:9], v26, s27, v[4:5]
	v_mad_u64_u32 v[28:29], s[8:9], v28, s27, v[4:5]
	v_mad_u64_u32 v[30:31], s[8:9], v30, s27, v[4:5]
	v_mad_u64_u32 v[32:33], s[8:9], v32, s27, v[4:5]
	v_mad_u64_u32 v[34:35], s[8:9], v34, s27, v[4:5]
	v_mad_u64_u32 v[36:37], s[8:9], v36, s27, v[4:5]
	v_mad_u64_u32 v[38:39], s[8:9], v38, s27, v[4:5]
	v_mad_u64_u32 v[40:41], s[8:9], v40, s27, v[4:5]
	v_mad_u64_u32 v[42:43], s[8:9], v42, s27, v[4:5]
	v_mad_u64_u32 v[44:45], s[8:9], v44, s27, v[4:5]
	s_waitcnt vmcnt(0)
	ds_write_b32 v14, v9
	ds_write_b32 v16, v46
	ds_write_b32 v18, v47
	ds_write_b32 v20, v48
	ds_write_b32 v22, v49
	ds_write_b32 v24, v50
	ds_write_b32 v26, v51
	ds_write_b32 v28, v52
	ds_write_b32 v30, v53
	ds_write_b32 v32, v54
	ds_write_b32 v34, v55
	ds_write_b32 v36, v56
	ds_write_b32 v38, v57
	ds_write_b32 v40, v58
	ds_write_b32 v42, v59
	ds_write_b32 v44, v60
	s_cbranch_scc1 .LBB0_457
; #define LAS __attribute__((address_space(3)))
; __device__ __forceinline__ unsigned cvtpk(float lo, float hi) { return pg8::cvt_pk_bf16(lo, hi); }
; __device__ __forceinline__ float bflo(unsigned w) { return __uint_as_float(w << 16); }
; __device__ __forceinline__ float bfhi(unsigned w) { return __uint_as_float(w & 0xffff0000u); }
; __device__ __forceinline__ void transpose_item(const float* __restrict__ W, int K, int N, bf16* __restrict__ WT, LAS float* scr, int item, int lane) {
;     ...
;     const int c = lane & 7;
; #pragma unroll
;     for (int j = 0; j < 4; ++j) { const int n = (lane >> 3) + 8 * j; const LAS float* s = scr + (8 * c) * 33 + n;
;         v4u o; o.x = cvtpk(s[0 * 33], s[1 * 33]); o.y = cvtpk(s[2 * 33], s[3 * 33]); o.z = cvtpk(s[4 * 33], s[5 * 33]); o.w = cvtpk(s[6 * 33], s[7 * 33]);
;         *(v4u*)(WT + (size_t)(n0 + n) * K + k0 + 8 * c) = o; }
; __device__ __forceinline__ void fold_rows(const bf16* __restrict__ Wt, const float* __restrict__ g, const float* __restrict__ b, float* __restrict__ c, float* __restrict__ d, int r0, int r1, int lane) {
;     ...
;         for (int j = 0; j < 4; ++j)
; #pragma unroll
;             for (int e = 0; e < 4; ++e) { const float lo = bflo(w[j][e]), hi = bfhi(w[j][e]); cs += gr[j][2 * e] * lo + gr[j][2 * e + 1] * hi; ds += br[j][2 * e] * lo + br[j][2 * e + 1] * hi; }
	s_mul_hi_i32 s1, s0, 0x1400000
	s_mul_i32 s0, s0, 0x1400000
	v_readlane_b32 s5, v253, 48
	s_waitcnt lgkmcnt(0)
	s_add_u32 s5, s5, s0
	v_readlane_b32 s0, v253, 49
	ds_read2_b32 v[18:19], v5 offset0:33 offset1:41
	ds_read2_b32 v[20:21], v5 offset1:8
	ds_read2_b32 v[22:23], v5 offset0:66 offset1:74
	ds_read2_b32 v[24:25], v5 offset0:99 offset1:107
	ds_read2_b32 v[26:27], v5 offset0:132 offset1:140
	ds_read2_b32 v[28:29], v5 offset0:165 offset1:173
	ds_read2_b32 v[30:31], v5 offset0:198 offset1:206
	ds_read2_b32 v[32:33], v5 offset0:231 offset1:239
	s_addc_u32 s6, s0, s1
	s_lshl_b64 s[0:1], s[34:35], 1
	s_add_u32 s0, s5, s0
	v_or_b32_e32 v34, s30, v3
	s_addc_u32 s1, s6, s1
	v_lshlrev_b32_e32 v10, 1, v6
	v_mov_b32_e32 v11, v85
	v_ashrrev_i32_e32 v35, 31, v34
	v_lshl_add_u64 v[10:11], s[0:1], 0, v[10:11]
	v_lshlrev_b64 v[34:35], 12, v[34:35]
	s_waitcnt lgkmcnt(6)
	v_cvt_pk_bf16_f32 v14, v20, v18
	s_waitcnt lgkmcnt(4)
	v_cvt_pk_bf16_f32 v15, v22, v24
	s_waitcnt lgkmcnt(2)
	v_cvt_pk_bf16_f32 v16, v26, v28
	s_waitcnt lgkmcnt(0)
	v_cvt_pk_bf16_f32 v17, v30, v32
	v_lshl_add_u64 v[34:35], v[10:11], 0, v[34:35]
	v_or_b32_e32 v18, s30, v7
	global_store_dwordx4 v[34:35], v[14:17], off
	v_lshlrev_b32_e32 v110, 16, v14
	v_and_b32_e32 v111, 0xffff0000, v14
	v_lshlrev_b32_e32 v112, 16, v15
	v_and_b32_e32 v113, 0xffff0000, v15
	v_lshlrev_b32_e32 v114, 16, v16
	v_and_b32_e32 v115, 0xffff0000, v16
	v_lshlrev_b32_e32 v116, 16, v17
	v_and_b32_e32 v117, 0xffff0000, v17
	v_mul_f32_e32 v118, v94, v110
	v_mul_f32_e32 v119, v102, v110
	v_fmac_f32_e32 v118, v95, v111
	v_fmac_f32_e32 v119, v103, v111
	v_fmac_f32_e32 v118, v96, v112
	v_fmac_f32_e32 v119, v104, v112
	v_fmac_f32_e32 v118, v97, v113
	v_fmac_f32_e32 v119, v105, v113
	v_fmac_f32_e32 v118, v98, v114
	v_fmac_f32_e32 v119, v106, v114
	v_fmac_f32_e32 v118, v99, v115
	v_fmac_f32_e32 v119, v107, v115
	v_fmac_f32_e32 v118, v100, v116
	v_fmac_f32_e32 v119, v108, v116
	v_fmac_f32_e32 v118, v101, v117
	v_fmac_f32_e32 v119, v109, v117
	v_readlane_b32 s50, v254, 61
	v_readlane_b32 s12, v255, 0
	v_cvt_pk_bf16_f32 v14, v21, v19
	v_ashrrev_i32_e32 v19, 31, v18
	v_cvt_pk_bf16_f32 v15, v23, v25
	v_cvt_pk_bf16_f32 v16, v27, v29
	v_cvt_pk_bf16_f32 v17, v31, v33
	v_lshlrev_b64 v[18:19], 12, v[18:19]
	ds_read2_b32 v[20:21], v5 offset0:49 offset1:57
	ds_read2_b32 v[22:23], v5 offset0:16 offset1:24
	ds_read2_b32 v[24:25], v5 offset0:82 offset1:90
	ds_read2_b32 v[26:27], v5 offset0:115 offset1:123
	ds_read2_b32 v[28:29], v5 offset0:148 offset1:156
	ds_read2_b32 v[30:31], v5 offset0:181 offset1:189
	ds_read2_b32 v[32:33], v5 offset0:214 offset1:222
	ds_read2_b32 v[34:35], v5 offset0:247 offset1:255
	v_lshl_add_u64 v[18:19], v[10:11], 0, v[18:19]
	global_store_dwordx4 v[18:19], v[14:17], off
	v_lshlrev_b32_e32 v110, 16, v14
	v_and_b32_e32 v111, 0xffff0000, v14
	v_lshlrev_b32_e32 v112, 16, v15
	v_and_b32_e32 v113, 0xffff0000, v15
	v_lshlrev_b32_e32 v114, 16, v16
	v_and_b32_e32 v115, 0xffff0000, v16
	v_lshlrev_b32_e32 v116, 16, v17
	v_and_b32_e32 v117, 0xffff0000, v17
	v_mul_f32_e32 v120, v94, v110
	v_mul_f32_e32 v121, v102, v110
	v_fmac_f32_e32 v120, v95, v111
	v_fmac_f32_e32 v121, v103, v111
	v_fmac_f32_e32 v120, v96, v112
	v_fmac_f32_e32 v121, v104, v112
	v_fmac_f32_e32 v120, v97, v113
	v_fmac_f32_e32 v121, v105, v113
	v_fmac_f32_e32 v120, v98, v114
	v_fmac_f32_e32 v121, v106, v114
	v_fmac_f32_e32 v120, v99, v115
	v_fmac_f32_e32 v121, v107, v115
	v_fmac_f32_e32 v120, v100, v116
	v_fmac_f32_e32 v121, v108, v116
	v_fmac_f32_e32 v120, v101, v117
	v_fmac_f32_e32 v121, v109, v117
	v_or_b32_e32 v18, s30, v12
	v_ashrrev_i32_e32 v19, 31, v18
	v_lshlrev_b64 v[18:19], 12, v[18:19]
	s_waitcnt lgkmcnt(6)
	v_cvt_pk_bf16_f32 v14, v22, v20
	s_waitcnt lgkmcnt(4)
	v_cvt_pk_bf16_f32 v15, v24, v26
	s_waitcnt lgkmcnt(2)
	v_cvt_pk_bf16_f32 v16, v28, v30
	s_waitcnt lgkmcnt(0)
; #define LAS __attribute__((address_space(3)))
; __device__ __forceinline__ unsigned cvtpk(float lo, float hi) { return pg8::cvt_pk_bf16(lo, hi); }
; __device__ __forceinline__ void transpose_item(const float* __restrict__ W, int K, int N, bf16* __restrict__ WT, LAS float* scr, int item, int lane) {
;     ...
;     for (int j = 0; j < 4; ++j) { const int n = (lane >> 3) + 8 * j; const LAS float* s = scr + (8 * c) * 33 + n;
;         v4u o; o.x = cvtpk(s[0 * 33], s[1 * 33]); o.y = cvtpk(s[2 * 33], s[3 * 33]); o.z = cvtpk(s[4 * 33], s[5 * 33]); o.w = cvtpk(s[6 * 33], s[7 * 33]);
;         *(v4u*)(WT + (size_t)(n0 + n) * K + k0 + 8 * c) = o; }
;     asm volatile("s_waitcnt lgkmcnt(0)" ::: "memory");
; __device__ __forceinline__ void fold_rows(const bf16* __restrict__ Wt, const float* __restrict__ g, const float* __restrict__ b, float* __restrict__ c, float* __restrict__ d, int r0, int r1, int lane) {
;     ...
;         cs = wave_sum(cs); ds = wave_sum(ds);
;         if (lane == 0) { c[r] = cs; d[r] = ds; } }
	v_cvt_pk_bf16_f32 v17, v32, v34
	v_lshl_add_u64 v[18:19], v[10:11], 0, v[18:19]
	global_store_dwordx4 v[18:19], v[14:17], off
	v_lshlrev_b32_e32 v110, 16, v14
	v_and_b32_e32 v111, 0xffff0000, v14
	v_lshlrev_b32_e32 v112, 16, v15
	v_and_b32_e32 v113, 0xffff0000, v15
	v_lshlrev_b32_e32 v114, 16, v16
	v_and_b32_e32 v115, 0xffff0000, v16
	v_lshlrev_b32_e32 v116, 16, v17
	v_and_b32_e32 v117, 0xffff0000, v17
	v_mul_f32_e32 v122, v94, v110
	v_mul_f32_e32 v123, v102, v110
	v_fmac_f32_e32 v122, v95, v111
	v_fmac_f32_e32 v123, v103, v111
	v_fmac_f32_e32 v122, v96, v112
	v_fmac_f32_e32 v123, v104, v112
	v_fmac_f32_e32 v122, v97, v113
	v_fmac_f32_e32 v123, v105, v113
	v_fmac_f32_e32 v122, v98, v114
	v_fmac_f32_e32 v123, v106, v114
	v_fmac_f32_e32 v122, v99, v115
	v_fmac_f32_e32 v123, v107, v115
	v_fmac_f32_e32 v122, v100, v116
	v_fmac_f32_e32 v123, v108, v116
	v_fmac_f32_e32 v122, v101, v117
	v_fmac_f32_e32 v123, v109, v117
	v_or_b32_e32 v18, s30, v13
	v_ashrrev_i32_e32 v19, 31, v18
	v_lshlrev_b64 v[18:19], 12, v[18:19]
	v_cvt_pk_bf16_f32 v14, v23, v21
	v_cvt_pk_bf16_f32 v15, v25, v27
	v_cvt_pk_bf16_f32 v16, v29, v31
	v_cvt_pk_bf16_f32 v17, v33, v35
	v_lshl_add_u64 v[10:11], v[10:11], 0, v[18:19]
	global_store_dwordx4 v[10:11], v[14:17], off
	v_lshlrev_b32_e32 v110, 16, v14
	v_and_b32_e32 v111, 0xffff0000, v14
	v_lshlrev_b32_e32 v112, 16, v15
	v_and_b32_e32 v113, 0xffff0000, v15
	v_lshlrev_b32_e32 v114, 16, v16
	v_and_b32_e32 v115, 0xffff0000, v16
	v_lshlrev_b32_e32 v116, 16, v17
	v_and_b32_e32 v117, 0xffff0000, v17
	v_mul_f32_e32 v124, v94, v110
	v_mul_f32_e32 v125, v102, v110
	v_fmac_f32_e32 v124, v95, v111
	v_fmac_f32_e32 v125, v103, v111
	v_fmac_f32_e32 v124, v96, v112
	v_fmac_f32_e32 v125, v104, v112
	v_fmac_f32_e32 v124, v97, v113
	v_fmac_f32_e32 v125, v105, v113
	v_fmac_f32_e32 v124, v98, v114
	v_fmac_f32_e32 v125, v106, v114
	v_fmac_f32_e32 v124, v99, v115
	v_fmac_f32_e32 v125, v107, v115
	v_fmac_f32_e32 v124, v100, v116
	v_fmac_f32_e32 v125, v108, v116
	v_fmac_f32_e32 v124, v101, v117
	v_fmac_f32_e32 v125, v109, v117
	v_add_f32_dpp v118, v118, v118 quad_perm:[1,0,3,2] row_mask:0xf bank_mask:0xf
	v_add_f32_dpp v119, v119, v119 quad_perm:[1,0,3,2] row_mask:0xf bank_mask:0xf
	v_add_f32_dpp v120, v120, v120 quad_perm:[1,0,3,2] row_mask:0xf bank_mask:0xf
	v_add_f32_dpp v121, v121, v121 quad_perm:[1,0,3,2] row_mask:0xf bank_mask:0xf
	v_add_f32_dpp v122, v122, v122 quad_perm:[1,0,3,2] row_mask:0xf bank_mask:0xf
	v_add_f32_dpp v123, v123, v123 quad_perm:[1,0,3,2] row_mask:0xf bank_mask:0xf
	v_add_f32_dpp v124, v124, v124 quad_perm:[1,0,3,2] row_mask:0xf bank_mask:0xf
	v_add_f32_dpp v125, v125, v125 quad_perm:[1,0,3,2] row_mask:0xf bank_mask:0xf
	v_add_f32_dpp v118, v118, v118 quad_perm:[2,3,0,1] row_mask:0xf bank_mask:0xf
	v_add_f32_dpp v119, v119, v119 quad_perm:[2,3,0,1] row_mask:0xf bank_mask:0xf
	v_add_f32_dpp v120, v120, v120 quad_perm:[2,3,0,1] row_mask:0xf bank_mask:0xf
	v_add_f32_dpp v121, v121, v121 quad_perm:[2,3,0,1] row_mask:0xf bank_mask:0xf
	v_add_f32_dpp v122, v122, v122 quad_perm:[2,3,0,1] row_mask:0xf bank_mask:0xf
	v_add_f32_dpp v123, v123, v123 quad_perm:[2,3,0,1] row_mask:0xf bank_mask:0xf
	v_add_f32_dpp v124, v124, v124 quad_perm:[2,3,0,1] row_mask:0xf bank_mask:0xf
	v_add_f32_dpp v125, v125, v125 quad_perm:[2,3,0,1] row_mask:0xf bank_mask:0xf
	v_add_f32_dpp v118, v118, v118 row_half_mirror row_mask:0xf bank_mask:0xf
	v_add_f32_dpp v119, v119, v119 row_half_mirror row_mask:0xf bank_mask:0xf
	v_add_f32_dpp v120, v120, v120 row_half_mirror row_mask:0xf bank_mask:0xf
	v_add_f32_dpp v121, v121, v121 row_half_mirror row_mask:0xf bank_mask:0xf
	v_add_f32_dpp v122, v122, v122 row_half_mirror row_mask:0xf bank_mask:0xf
	v_add_f32_dpp v123, v123, v123 row_half_mirror row_mask:0xf bank_mask:0xf
	v_add_f32_dpp v124, v124, v124 row_half_mirror row_mask:0xf bank_mask:0xf
	v_add_f32_dpp v125, v125, v125 row_half_mirror row_mask:0xf bank_mask:0xf
	v_cmp_eq_u32_e32 vcc, 0, v6
	s_and_saveexec_b64 s[36:37], vcc
	s_lshl_b32 s100, s101, 5
	s_lshr_b32 s38, s34, 6
	s_add_i32 s100, s100, s38
	s_mul_i32 s100, s100, 0x1400
	s_add_i32 s100, s100, s30
	s_lshl_b32 s100, s100, 3
	s_add_u32 s38, s20, 0x1ac00000
	s_addc_u32 s39, s21, 0
	v_lshlrev_b32_e32 v126, 3, v3
	v_add_u32_e32 v126, s100, v126
	global_store_dwordx2 v126, v[118:119], s[38:39]
	global_store_dwordx2 v126, v[120:121], s[38:39] offset:64
	global_store_dwordx2 v126, v[122:123], s[38:39] offset:128
	global_store_dwordx2 v126, v[124:125], s[38:39] offset:192
	s_or_b64 exec, exec, s[36:37]
	s_waitcnt lgkmcnt(0)
	s_movk_i32 s17, 0x1000
	v_readlane_b32 s51, v254, 62
	v_readlane_b32 s13, v255, 1
	s_branch .LBB0_438

; __device__ __forceinline__ unsigned cvtpk(float lo, float hi) { return pg8::cvt_pk_bf16(lo, hi); }
; __device__ __forceinline__ void prologue(const Args& a, LAS unsigned char* lds, int G, const int tid_in) {
;     ...
;     { const f32x4* xs = (const f32x4*)a.in[0]; v2u* xo = (v2u*)(ws + WS_XBF);
;       for (int idx = gt; idx < T * D / 4; idx += NT_) { const f32x4 v = xs[idx]; v2u o; o.x = cvtpk(v.x, v.y); o.y = cvtpk(v.z, v.w); xo[idx] = o; } }
.LBB0_469:
	global_load_dwordx4 v[6:9], v[2:3], off nt
	v_add_u32_e32 v0, s12, v0
	s_mov_b32 s4, 0x3fffff
	v_cmp_lt_i32_e32 vcc, s4, v0
	v_lshl_add_u64 v[2:3], v[2:3], 0, s[6:7]
	s_or_b64 s[30:31], vcc, s[30:31]
	s_waitcnt vmcnt(0)
	v_cvt_pk_bf16_f32 v6, v6, v7
	v_cvt_pk_bf16_f32 v7, v8, v9
	global_store_dwordx2 v[4:5], v[6:7], off
	v_lshl_add_u64 v[4:5], v[4:5], 0, s[8:9]
	s_andn2_b64 exec, exec, s[30:31]
	s_cbranch_execnz .LBB0_469
	s_branch .LBB0_7
